# P0 weight-transpose loops: LDS-reuse barrier moved below the tile loads (loads issue before the barrier)
# speedup vs baseline: 1.0090x; 1.0066x over previous
; DEV unsigned pk2(float lo, float hi) { f32x2_t v = {lo, hi}; bf16x2_t b = __builtin_convertvector(v, bf16x2_t); return __builtin_bit_cast(unsigned, b); }
; DEV int tid_l() { int t = threadIdx.x; asm volatile("" : "+v"(t)); return t; }
; DEV void transpose_job(const float* __restrict__ W, int K, int N, int ldw, bf16_t* Wt, int ldt) {
;   float* tile = (float*)smem;
;   const int tid = tid_l(); const int ntn = N >> 6, ntiles = (K >> 6) * ntn;
;   for (int t = blockIdx.x; t < ntiles; t += gridDim.x) {
;     const int k0 = (t / ntn) << 6, n0 = (t % ntn) << 6;
;     __syncthreads();
; #pragma unroll
;     for (int q = 0; q < 2; ++q) {
;       const int id = tid + q * 512, i = id >> 4, c4 = (id & 15) << 2;
;       const f32x4 v = *(const f32x4*)(W + (size_t)(k0 + i) * ldw + n0 + c4);
;       tile[i * 65 + c4 + 0] = v[0]; tile[i * 65 + c4 + 1] = v[1]; tile[i * 65 + c4 + 2] = v[2]; tile[i * 65 + c4 + 3] = v[3];
;     }
;     __syncthreads();
;     const int n = tid >> 3, kc = (tid & 7) << 3;
;     u32x4 o;
;     o[0] = pk2(tile[(kc + 0) * 65 + n], tile[(kc + 1) * 65 + n]); o[1] = pk2(tile[(kc + 2) * 65 + n], tile[(kc + 3) * 65 + n]);
;     o[2] = pk2(tile[(kc + 4) * 65 + n], tile[(kc + 5) * 65 + n]); o[3] = pk2(tile[(kc + 6) * 65 + n], tile[(kc + 7) * 65 + n]);
;     *(u32x4*)(Wt + (size_t)(n0 + n) * ldt + k0 + kc) = o;
;   }
.LBB0_9:
	s_mul_hi_i32 s10, s9, 0x2aaaaaab
	s_lshr_b32 s11, s10, 31
	s_ashr_i32 s10, s10, 3
	s_add_i32 s11, s10, s11
	s_lshl_b32 s10, s11, 6
	s_mulk_i32 s11, 0xf400
	s_add_i32 s12, s6, s11
	s_ashr_i32 s13, s12, 31
	v_add_u32_e32 v14, s10, v7
	v_lshl_add_u64 v[12:13], s[12:13], 2, v[4:5]
	v_add_u32_e32 v15, s10, v8
	v_mad_i64_i32 v[20:21], s[14:15], v14, s8, v[12:13]
	v_mad_i64_i32 v[22:23], s[14:15], v15, s8, v[12:13]
	global_load_dwordx4 v[12:15], v[20:21], off
	global_load_dwordx4 v[16:19], v[22:23], off
	v_add_u32_e32 v20, s12, v1
	v_ashrrev_i32_e32 v21, 31, v20
	v_lshlrev_b64 v[20:21], 11, v[20:21]
	s_ashr_i32 s11, s10, 31
	v_lshl_add_u64 v[20:21], s[2:3], 0, v[20:21]
	s_add_i32 s9, s9, s86
	s_add_i32 s6, s6, s7
	v_lshl_add_u64 v[20:21], s[10:11], 1, v[20:21]
	s_cmpk_lt_i32 s9, 0x300
	v_lshl_add_u64 v[20:21], v[20:21], 0, v[2:3]
	s_barrier
	s_waitcnt vmcnt(1)
	ds_write2_b32 v9, v12, v13 offset1:1
	ds_write2_b32 v9, v14, v15 offset0:2 offset1:3
	s_waitcnt vmcnt(0)
	ds_write2_b32 v10, v16, v17 offset1:1
	ds_write2_b32 v10, v18, v19 offset0:2 offset1:3
	s_waitcnt lgkmcnt(0)
	s_barrier
	ds_read2_b32 v[12:13], v6 offset1:65
	ds_read2_b32 v[14:15], v6 offset0:130 offset1:195
	ds_read2_b32 v[16:17], v11 offset0:4 offset1:69
	ds_read2_b32 v[18:19], v11 offset0:134 offset1:199
	s_waitcnt lgkmcnt(3)
	v_cvt_pk_bf16_f32 v12, v12, v13
	s_waitcnt lgkmcnt(2)
	v_cvt_pk_bf16_f32 v13, v14, v15
	s_waitcnt lgkmcnt(1)
	v_cvt_pk_bf16_f32 v14, v16, v17
	s_waitcnt lgkmcnt(0)
	v_cvt_pk_bf16_f32 v15, v18, v19
	global_store_dwordx4 v[20:21], v[12:15], off
	s_cbranch_scc1 .LBB0_9

; DEV unsigned pk2(float lo, float hi) { f32x2_t v = {lo, hi}; bf16x2_t b = __builtin_convertvector(v, bf16x2_t); return __builtin_bit_cast(unsigned, b); }
; DEV int tid_l() { int t = threadIdx.x; asm volatile("" : "+v"(t)); return t; }
; DEV void transpose_job(const float* __restrict__ W, int K, int N, int ldw, bf16_t* Wt, int ldt) {
;   float* tile = (float*)smem;
;   const int tid = tid_l(); const int ntn = N >> 6, ntiles = (K >> 6) * ntn;
;   for (int t = blockIdx.x; t < ntiles; t += gridDim.x) {
;     const int k0 = (t / ntn) << 6, n0 = (t % ntn) << 6;
;     __syncthreads();
; #pragma unroll
;     for (int q = 0; q < 2; ++q) {
;       const int id = tid + q * 512, i = id >> 4, c4 = (id & 15) << 2;
;       const f32x4 v = *(const f32x4*)(W + (size_t)(k0 + i) * ldw + n0 + c4);
;       tile[i * 65 + c4 + 0] = v[0]; tile[i * 65 + c4 + 1] = v[1]; tile[i * 65 + c4 + 2] = v[2]; tile[i * 65 + c4 + 3] = v[3];
;     }
;     __syncthreads();
;     const int n = tid >> 3, kc = (tid & 7) << 3;
;     u32x4 o;
;     o[0] = pk2(tile[(kc + 0) * 65 + n], tile[(kc + 1) * 65 + n]); o[1] = pk2(tile[(kc + 2) * 65 + n], tile[(kc + 3) * 65 + n]);
;     o[2] = pk2(tile[(kc + 4) * 65 + n], tile[(kc + 5) * 65 + n]); o[3] = pk2(tile[(kc + 6) * 65 + n], tile[(kc + 7) * 65 + n]);
;     *(u32x4*)(Wt + (size_t)(n0 + n) * ldt + k0 + kc) = o;
;   }
.LBB0_12:
	s_ashr_i32 s15, s14, 31
	s_lshr_b32 s15, s15, 28
	s_add_i32 s15, s14, s15
	s_ashr_i32 s15, s15, 4
	s_lshl_b32 s16, s15, 6
	s_lshl_b32 s15, s15, 10
	s_sub_i32 s18, s12, s15
	v_add_u32_e32 v12, s16, v7
	v_add_u32_e32 v14, s16, v8
	s_ashr_i32 s19, s18, 31
	v_ashrrev_i32_e32 v13, 31, v12
	v_ashrrev_i32_e32 v15, 31, v14
	v_lshl_add_u64 v[16:17], s[18:19], 2, v[4:5]
	v_lshlrev_b64 v[12:13], 12, v[12:13]
	v_lshlrev_b64 v[14:15], 12, v[14:15]
	v_lshl_add_u64 v[12:13], v[16:17], 0, v[12:13]
	v_lshl_add_u64 v[16:17], v[16:17], 0, v[14:15]
	global_load_dwordx4 v[12:15], v[12:13], off
	s_nop 0
	global_load_dwordx4 v[16:19], v[16:17], off
	v_add_u32_e32 v20, s18, v1
	v_ashrrev_i32_e32 v21, 31, v20
	v_lshlrev_b64 v[20:21], 11, v[20:21]
	s_ashr_i32 s17, s16, 31
	v_lshl_add_u64 v[20:21], s[10:11], 0, v[20:21]
	s_add_i32 s14, s14, s86
	s_add_i32 s12, s12, s13
	v_lshl_add_u64 v[20:21], s[16:17], 1, v[20:21]
	s_cmpk_lt_i32 s14, 0x100
	v_lshl_add_u64 v[20:21], v[20:21], 0, v[2:3]
	s_barrier
	s_waitcnt vmcnt(1)
	ds_write2_b32 v9, v12, v13 offset1:1
	ds_write2_b32 v9, v14, v15 offset0:2 offset1:3
	s_waitcnt vmcnt(0)
	ds_write2_b32 v10, v16, v17 offset1:1
	ds_write2_b32 v10, v18, v19 offset0:2 offset1:3
	s_waitcnt lgkmcnt(0)
	s_barrier
	ds_read2_b32 v[12:13], v6 offset1:65
	ds_read2_b32 v[14:15], v6 offset0:130 offset1:195
	ds_read2_b32 v[16:17], v11 offset0:4 offset1:69
	ds_read2_b32 v[18:19], v11 offset0:134 offset1:199
	s_waitcnt lgkmcnt(3)
	v_cvt_pk_bf16_f32 v12, v12, v13
	s_waitcnt lgkmcnt(2)
	v_cvt_pk_bf16_f32 v13, v14, v15
	s_waitcnt lgkmcnt(1)
	v_cvt_pk_bf16_f32 v14, v16, v17
	s_waitcnt lgkmcnt(0)
	v_cvt_pk_bf16_f32 v15, v18, v19
	global_store_dwordx4 v[20:21], v[12:15], off
	s_cbranch_scc1 .LBB0_12

; DEV unsigned pk2(float lo, float hi) { f32x2_t v = {lo, hi}; bf16x2_t b = __builtin_convertvector(v, bf16x2_t); return __builtin_bit_cast(unsigned, b); }
; DEV int tid_l() { int t = threadIdx.x; asm volatile("" : "+v"(t)); return t; }
; DEV void transpose_job(const float* __restrict__ W, int K, int N, int ldw, bf16_t* Wt, int ldt) {
;   float* tile = (float*)smem;
;   const int tid = tid_l(); const int ntn = N >> 6, ntiles = (K >> 6) * ntn;
;   for (int t = blockIdx.x; t < ntiles; t += gridDim.x) {
;     const int k0 = (t / ntn) << 6, n0 = (t % ntn) << 6;
;     __syncthreads();
; #pragma unroll
;     for (int q = 0; q < 2; ++q) {
;       const int id = tid + q * 512, i = id >> 4, c4 = (id & 15) << 2;
;       const f32x4 v = *(const f32x4*)(W + (size_t)(k0 + i) * ldw + n0 + c4);
;       tile[i * 65 + c4 + 0] = v[0]; tile[i * 65 + c4 + 1] = v[1]; tile[i * 65 + c4 + 2] = v[2]; tile[i * 65 + c4 + 3] = v[3];
;     }
;     __syncthreads();
;     const int n = tid >> 3, kc = (tid & 7) << 3;
;     u32x4 o;
;     o[0] = pk2(tile[(kc + 0) * 65 + n], tile[(kc + 1) * 65 + n]); o[1] = pk2(tile[(kc + 2) * 65 + n], tile[(kc + 3) * 65 + n]);
;     o[2] = pk2(tile[(kc + 4) * 65 + n], tile[(kc + 5) * 65 + n]); o[3] = pk2(tile[(kc + 6) * 65 + n], tile[(kc + 7) * 65 + n]);
;     *(u32x4*)(Wt + (size_t)(n0 + n) * ldt + k0 + kc) = o;
;   }
.LBB0_15:
	s_ashr_i32 s15, s14, 31
	s_lshr_b32 s15, s15, 27
	s_add_i32 s15, s14, s15
	s_ashr_i32 s15, s15, 5
	s_lshl_b32 s16, s15, 6
	s_lshl_b32 s15, s15, 11
	s_sub_i32 s18, s12, s15
	v_add_u32_e32 v12, s16, v7
	v_add_u32_e32 v14, s16, v8
	s_ashr_i32 s19, s18, 31
	v_ashrrev_i32_e32 v13, 31, v12
	v_ashrrev_i32_e32 v15, 31, v14
	v_lshl_add_u64 v[16:17], s[18:19], 2, v[4:5]
	v_lshlrev_b64 v[12:13], 13, v[12:13]
	v_lshlrev_b64 v[14:15], 13, v[14:15]
	v_lshl_add_u64 v[12:13], v[16:17], 0, v[12:13]
	v_lshl_add_u64 v[16:17], v[16:17], 0, v[14:15]
	global_load_dwordx4 v[12:15], v[12:13], off
	s_nop 0
	global_load_dwordx4 v[16:19], v[16:17], off
	v_add_u32_e32 v20, s18, v1
	v_ashrrev_i32_e32 v21, 31, v20
	v_lshlrev_b64 v[20:21], 11, v[20:21]
	s_ashr_i32 s17, s16, 31
	v_lshl_add_u64 v[20:21], s[10:11], 0, v[20:21]
	s_add_i32 s14, s14, s86
	s_add_i32 s12, s12, s13
	v_lshl_add_u64 v[20:21], s[16:17], 1, v[20:21]
	s_cmpk_lt_i32 s14, 0x200
	v_lshl_add_u64 v[20:21], v[20:21], 0, v[2:3]
	s_barrier
	s_waitcnt vmcnt(1)
	ds_write2_b32 v9, v12, v13 offset1:1
	ds_write2_b32 v9, v14, v15 offset0:2 offset1:3
	s_waitcnt vmcnt(0)
	ds_write2_b32 v10, v16, v17 offset1:1
	ds_write2_b32 v10, v18, v19 offset0:2 offset1:3
	s_waitcnt lgkmcnt(0)
	s_barrier
	ds_read2_b32 v[12:13], v6 offset1:65
	ds_read2_b32 v[14:15], v6 offset0:130 offset1:195
	ds_read2_b32 v[16:17], v11 offset0:4 offset1:69
	ds_read2_b32 v[18:19], v11 offset0:134 offset1:199
	s_waitcnt lgkmcnt(3)
	v_cvt_pk_bf16_f32 v12, v12, v13
	s_waitcnt lgkmcnt(2)
	v_cvt_pk_bf16_f32 v13, v14, v15
	s_waitcnt lgkmcnt(1)
	v_cvt_pk_bf16_f32 v14, v16, v17
	s_waitcnt lgkmcnt(0)
	v_cvt_pk_bf16_f32 v15, v18, v19
	global_store_dwordx4 v[20:21], v[12:15], off
	s_cbranch_scc1 .LBB0_15

; DEV unsigned pk2(float lo, float hi) { f32x2_t v = {lo, hi}; bf16x2_t b = __builtin_convertvector(v, bf16x2_t); return __builtin_bit_cast(unsigned, b); }
; DEV int tid_l() { int t = threadIdx.x; asm volatile("" : "+v"(t)); return t; }
; DEV void transpose_job(const float* __restrict__ W, int K, int N, int ldw, bf16_t* Wt, int ldt) {
;   float* tile = (float*)smem;
;   const int tid = tid_l(); const int ntn = N >> 6, ntiles = (K >> 6) * ntn;
;   for (int t = blockIdx.x; t < ntiles; t += gridDim.x) {
;     const int k0 = (t / ntn) << 6, n0 = (t % ntn) << 6;
;     __syncthreads();
; #pragma unroll
;     for (int q = 0; q < 2; ++q) {
;       const int id = tid + q * 512, i = id >> 4, c4 = (id & 15) << 2;
;       const f32x4 v = *(const f32x4*)(W + (size_t)(k0 + i) * ldw + n0 + c4);
;       tile[i * 65 + c4 + 0] = v[0]; tile[i * 65 + c4 + 1] = v[1]; tile[i * 65 + c4 + 2] = v[2]; tile[i * 65 + c4 + 3] = v[3];
;     }
;     __syncthreads();
;     const int n = tid >> 3, kc = (tid & 7) << 3;
;     u32x4 o;
;     o[0] = pk2(tile[(kc + 0) * 65 + n], tile[(kc + 1) * 65 + n]); o[1] = pk2(tile[(kc + 2) * 65 + n], tile[(kc + 3) * 65 + n]);
;     o[2] = pk2(tile[(kc + 4) * 65 + n], tile[(kc + 5) * 65 + n]); o[3] = pk2(tile[(kc + 6) * 65 + n], tile[(kc + 7) * 65 + n]);
;     *(u32x4*)(Wt + (size_t)(n0 + n) * ldt + k0 + kc) = o;
;   }
.LBB0_20:
	s_ashr_i32 s11, s10, 31
	s_lshr_b32 s11, s11, 28
	s_add_i32 s11, s10, s11
	s_ashr_i32 s11, s11, 4
	s_lshl_b32 s14, s11, 6
	s_lshl_b32 s11, s11, 10
	s_sub_i32 s16, s7, s11
	v_add_u32_e32 v12, s14, v7
	v_add_u32_e32 v14, s14, v8
	s_ashr_i32 s17, s16, 31
	v_ashrrev_i32_e32 v13, 31, v12
	v_ashrrev_i32_e32 v15, 31, v14
	v_lshl_add_u64 v[16:17], s[16:17], 2, v[4:5]
	v_lshlrev_b64 v[12:13], 12, v[12:13]
	v_lshlrev_b64 v[14:15], 12, v[14:15]
	v_lshl_add_u64 v[12:13], v[16:17], 0, v[12:13]
	v_lshl_add_u64 v[16:17], v[16:17], 0, v[14:15]
	global_load_dwordx4 v[12:15], v[12:13], off
	s_nop 0
	global_load_dwordx4 v[16:19], v[16:17], off
	v_add_u32_e32 v20, s16, v1
	v_ashrrev_i32_e32 v21, 31, v20
	v_lshlrev_b64 v[20:21], 11, v[20:21]
	s_ashr_i32 s15, s14, 31
	v_lshl_add_u64 v[20:21], s[0:1], 0, v[20:21]
	s_add_i32 s10, s10, s86
	s_add_i32 s7, s7, s6
	v_lshl_add_u64 v[20:21], s[14:15], 1, v[20:21]
	s_cmpk_lt_i32 s10, 0x100
	v_lshl_add_u64 v[20:21], v[20:21], 0, v[2:3]
	s_barrier
	s_waitcnt vmcnt(1)
	ds_write2_b32 v9, v12, v13 offset1:1
	ds_write2_b32 v9, v14, v15 offset0:2 offset1:3
	s_waitcnt vmcnt(0)
	ds_write2_b32 v10, v16, v17 offset1:1
	ds_write2_b32 v10, v18, v19 offset0:2 offset1:3
	s_waitcnt lgkmcnt(0)
	s_barrier
	ds_read2_b32 v[12:13], v6 offset1:65
	ds_read2_b32 v[14:15], v6 offset0:130 offset1:195
	ds_read2_b32 v[16:17], v11 offset0:4 offset1:69
	ds_read2_b32 v[18:19], v11 offset0:134 offset1:199
	s_waitcnt lgkmcnt(3)
	v_cvt_pk_bf16_f32 v12, v12, v13
	s_waitcnt lgkmcnt(2)
	v_cvt_pk_bf16_f32 v13, v14, v15
	s_waitcnt lgkmcnt(1)
	v_cvt_pk_bf16_f32 v14, v16, v17
	s_waitcnt lgkmcnt(0)
	v_cvt_pk_bf16_f32 v15, v18, v19
	global_store_dwordx4 v[20:21], v[12:15], off
	s_cbranch_scc1 .LBB0_20

; DEV unsigned pk2(float lo, float hi) { f32x2_t v = {lo, hi}; bf16x2_t b = __builtin_convertvector(v, bf16x2_t); return __builtin_bit_cast(unsigned, b); }
; DEV void transpose_job(const float* __restrict__ W, int K, int N, int ldw, bf16_t* Wt, int ldt) {
;     ...
;   for (int t = blockIdx.x; t < ntiles; t += gridDim.x) {
;     const int k0 = (t / ntn) << 6, n0 = (t % ntn) << 6;
;     __syncthreads();
; #pragma unroll
;     for (int q = 0; q < 2; ++q) {
;       const int id = tid + q * 512, i = id >> 4, c4 = (id & 15) << 2;
;       const f32x4 v = *(const f32x4*)(W + (size_t)(k0 + i) * ldw + n0 + c4);
;       tile[i * 65 + c4 + 0] = v[0]; tile[i * 65 + c4 + 1] = v[1]; tile[i * 65 + c4 + 2] = v[2]; tile[i * 65 + c4 + 3] = v[3];
;     }
;     __syncthreads();
;     const int n = tid >> 3, kc = (tid & 7) << 3;
;     u32x4 o;
;     o[0] = pk2(tile[(kc + 0) * 65 + n], tile[(kc + 1) * 65 + n]); o[1] = pk2(tile[(kc + 2) * 65 + n], tile[(kc + 3) * 65 + n]);
;     o[2] = pk2(tile[(kc + 4) * 65 + n], tile[(kc + 5) * 65 + n]); o[3] = pk2(tile[(kc + 6) * 65 + n], tile[(kc + 7) * 65 + n]);
;     *(u32x4*)(Wt + (size_t)(n0 + n) * ldt + k0 + kc) = o;
.LBB0_25:
	s_ashr_i32 s21, s20, 31
	s_lshr_b32 s21, s21, 28
	s_add_i32 s21, s20, s21
	s_ashr_i32 s21, s21, 4
	s_lshl_b32 s22, s21, 6
	s_lshl_b32 s21, s21, 10
	s_sub_i32 s24, s19, s21
	v_add_u32_e32 v12, s22, v7
	v_add_u32_e32 v14, s22, v8
	s_ashr_i32 s25, s24, 31
	v_ashrrev_i32_e32 v13, 31, v12
	v_ashrrev_i32_e32 v15, 31, v14
	v_lshl_add_u64 v[16:17], s[24:25], 2, v[4:5]
	v_lshlrev_b64 v[12:13], 12, v[12:13]
	v_lshlrev_b64 v[14:15], 12, v[14:15]
	v_lshl_add_u64 v[12:13], v[16:17], 0, v[12:13]
	v_lshl_add_u64 v[16:17], v[16:17], 0, v[14:15]
	global_load_dwordx4 v[12:15], v[12:13], off
	s_nop 0
	global_load_dwordx4 v[16:19], v[16:17], off
	v_add_u32_e32 v20, s24, v1
	v_ashrrev_i32_e32 v21, 31, v20
	v_lshlrev_b64 v[20:21], 9, v[20:21]
	s_ashr_i32 s23, s22, 31
	v_lshl_add_u64 v[20:21], s[10:11], 0, v[20:21]
	s_add_i32 s20, s20, s86
	s_add_i32 s19, s19, s18
	v_lshl_add_u64 v[20:21], s[22:23], 1, v[20:21]
	s_cmp_lt_i32 s20, 64
	v_lshl_add_u64 v[20:21], v[20:21], 0, v[2:3]
	s_barrier
	s_waitcnt vmcnt(1)
	ds_write2_b32 v9, v12, v13 offset1:1
	ds_write2_b32 v9, v14, v15 offset0:2 offset1:3
	s_waitcnt vmcnt(0)
	ds_write2_b32 v10, v16, v17 offset1:1
	ds_write2_b32 v10, v18, v19 offset0:2 offset1:3
	s_waitcnt lgkmcnt(0)
	s_barrier
	ds_read2_b32 v[12:13], v6 offset1:65
	ds_read2_b32 v[14:15], v6 offset0:130 offset1:195
	ds_read2_b32 v[16:17], v11 offset0:4 offset1:69
	ds_read2_b32 v[18:19], v11 offset0:134 offset1:199
	s_waitcnt lgkmcnt(3)
	v_cvt_pk_bf16_f32 v12, v12, v13
	s_waitcnt lgkmcnt(2)
	v_cvt_pk_bf16_f32 v13, v14, v15
	s_waitcnt lgkmcnt(1)
	v_cvt_pk_bf16_f32 v14, v16, v17
	s_waitcnt lgkmcnt(0)
	v_cvt_pk_bf16_f32 v15, v18, v19
	global_store_dwordx4 v[20:21], v[12:15], off
	s_cbranch_scc1 .LBB0_25

; DEV unsigned pk2(float lo, float hi) { f32x2_t v = {lo, hi}; bf16x2_t b = __builtin_convertvector(v, bf16x2_t); return __builtin_bit_cast(unsigned, b); }
; DEV void transpose_job(const float* __restrict__ W, int K, int N, int ldw, bf16_t* Wt, int ldt) {
;     ...
;   for (int t = blockIdx.x; t < ntiles; t += gridDim.x) {
;     const int k0 = (t / ntn) << 6, n0 = (t % ntn) << 6;
;     __syncthreads();
; #pragma unroll
;     for (int q = 0; q < 2; ++q) {
;       const int id = tid + q * 512, i = id >> 4, c4 = (id & 15) << 2;
;       const f32x4 v = *(const f32x4*)(W + (size_t)(k0 + i) * ldw + n0 + c4);
;       tile[i * 65 + c4 + 0] = v[0]; tile[i * 65 + c4 + 1] = v[1]; tile[i * 65 + c4 + 2] = v[2]; tile[i * 65 + c4 + 3] = v[3];
;     }
;     __syncthreads();
;     const int n = tid >> 3, kc = (tid & 7) << 3;
;     u32x4 o;
;     o[0] = pk2(tile[(kc + 0) * 65 + n], tile[(kc + 1) * 65 + n]); o[1] = pk2(tile[(kc + 2) * 65 + n], tile[(kc + 3) * 65 + n]);
;     o[2] = pk2(tile[(kc + 4) * 65 + n], tile[(kc + 5) * 65 + n]); o[3] = pk2(tile[(kc + 6) * 65 + n], tile[(kc + 7) * 65 + n]);
;     *(u32x4*)(Wt + (size_t)(n0 + n) * ldt + k0 + kc) = o;
.LBB0_28:
	s_ashr_i32 s19, s9, 31
	s_lshr_b32 s19, s19, 28
	s_add_i32 s19, s9, s19
	s_ashr_i32 s19, s19, 4
	s_lshl_b32 s20, s19, 6
	s_lshl_b32 s19, s19, 10
	s_sub_i32 s22, s8, s19
	v_add_u32_e32 v12, s20, v7
	v_add_u32_e32 v14, s20, v8
	s_ashr_i32 s23, s22, 31
	v_ashrrev_i32_e32 v13, 31, v12
	v_ashrrev_i32_e32 v15, 31, v14
	v_lshl_add_u64 v[16:17], s[22:23], 2, v[4:5]
	v_lshlrev_b64 v[12:13], 12, v[12:13]
	v_lshlrev_b64 v[14:15], 12, v[14:15]
	v_lshl_add_u64 v[12:13], v[16:17], 0, v[12:13]
	v_lshl_add_u64 v[16:17], v[16:17], 0, v[14:15]
	global_load_dwordx4 v[12:15], v[12:13], off
	s_nop 0
	global_load_dwordx4 v[16:19], v[16:17], off
	v_add_u32_e32 v20, s22, v1
	v_ashrrev_i32_e32 v21, 31, v20
	v_lshlrev_b64 v[20:21], 11, v[20:21]
	s_ashr_i32 s21, s20, 31
	v_lshl_add_u64 v[20:21], s[10:11], 0, v[20:21]
	s_add_i32 s9, s9, s86
	s_add_i32 s8, s8, s18
	v_lshl_add_u64 v[20:21], s[20:21], 1, v[20:21]
	s_cmpk_lt_i32 s9, 0x100
	v_lshl_add_u64 v[20:21], v[20:21], 0, v[2:3]
	s_barrier
	s_waitcnt vmcnt(1)
	ds_write2_b32 v9, v12, v13 offset1:1
	ds_write2_b32 v9, v14, v15 offset0:2 offset1:3
	s_waitcnt vmcnt(0)
	ds_write2_b32 v10, v16, v17 offset1:1
	ds_write2_b32 v10, v18, v19 offset0:2 offset1:3
	s_waitcnt lgkmcnt(0)
	s_barrier
	ds_read2_b32 v[12:13], v6 offset1:65
	ds_read2_b32 v[14:15], v6 offset0:130 offset1:195
	ds_read2_b32 v[16:17], v11 offset0:4 offset1:69
	ds_read2_b32 v[18:19], v11 offset0:134 offset1:199
	s_waitcnt lgkmcnt(3)
	v_cvt_pk_bf16_f32 v12, v12, v13
	s_waitcnt lgkmcnt(2)
	v_cvt_pk_bf16_f32 v13, v14, v15
	s_waitcnt lgkmcnt(1)
	v_cvt_pk_bf16_f32 v14, v16, v17
	s_waitcnt lgkmcnt(0)
	v_cvt_pk_bf16_f32 v15, v18, v19
	global_store_dwordx4 v[20:21], v[12:15], off
	s_cbranch_scc1 .LBB0_28
	s_branch .LBB0_22
